# nt cache policy on in-proj GEMM epilogue stores and out-GEMM x loads; hand-written final LayerNorm loop (hoisted gamma/beta, next-row prefetch, DPP wave sums)
# speedup vs baseline: 1.0207x; 1.0112x over previous
; __device__ __forceinline__ unsigned pkh2(float lo, float hi) { const f32x2 v = {lo, hi}; const f16x2_t h = __builtin_convertvector(v, f16x2_t); return __builtin_bit_cast(unsigned, h); }
;     __device__ __forceinline__ void operator()(const f32x4 (&acc)[2][2][4][2], const pg8::Unit& u, int wr, int wc, int fr, int fq) const {
;         const int row0 = u.pm * 256 + wr * 64 + fr, col0 = u.pn * 256 + wc * 32 + 8 * fq;
;         const int b = (u.pm * 256) >> 14;
;         f32x4 gt[2][2];
; #pragma unroll
;         for (int bj = 0; bj < 2; ++bj)
; #pragma unroll
;             for (int n = 0; n < 2; ++n) gt[bj][n] = *(const f32x4*)(MOD + b * 6144 + 4096 + col0 + bj * 128 + 4 * n) + *(const f32x4*)(b_mod + 4096 + col0 + bj * 128 + 4 * n);
; #pragma unroll
;         for (int ai = 0; ai < 2; ++ai)
; #pragma unroll
;           for (int mp = 0; mp < 2; ++mp) {
;             f32x4 xb[2][2][2];
; #pragma unroll
;             for (int mm = 0; mm < 2; ++mm)
; #pragma unroll
;                 for (int bj = 0; bj < 2; ++bj)
; #pragma unroll
;                     for (int n = 0; n < 2; ++n) xb[mm][bj][n] = *(const f32x4*)(x + (size_t)(row0 + ai * 128 + (mp * 2 + mm) * 16) * 2048 + col0 + bj * 128 + 4 * n);
;             asm volatile("" ::: "memory");
; #pragma unroll
;             for (int mm = 0; mm < 2; ++mm) { const int m = mp * 2 + mm; const size_t ro = (size_t)(row0 + ai * 128 + m * 16) * 2048 + col0;
; #pragma unroll
;                 for (int bj = 0; bj < 2; ++bj) {
;                     const f32x4 v0 = xb[mm][bj][0] * 1.189207115002721f + gt[bj][0] * acc[ai][bj][m][0], v1 = xb[mm][bj][1] * 1.189207115002721f + gt[bj][1] * acc[ai][bj][m][1];
;                     u32x4 w; w.x = pkh2(v0[0], v0[1]); w.y = pkh2(v0[2], v0[3]); w.z = pkh2(v1[0], v1[1]); w.w = pkh2(v1[2], v1[3]);
;                     *(u32x4*)(out + ro + bj * 128) = w; } }
;           }
;     }
.LBB0_946:
	v_lshl_or_b32 v144, s1, 8, v170
	s_lshr_b32 s1, s30, 6
	s_mul_i32 s34, s1, 0x1800
	s_ashr_i32 s35, s34, 31
	s_lshl_b64 s[34:35], s[34:35], 2
	s_add_u32 s34, s94, s34
	v_ashrrev_i32_e32 v145, 31, v144
	v_lshl_add_u32 v166, s30, 8, v168
	s_addc_u32 s35, s95, s35
	v_lshlrev_b64 v[146:147], 2, v[144:145]
	v_ashrrev_i32_e32 v167, 31, v166
	v_lshl_add_u64 v[162:163], s[34:35], 0, v[146:147]
	v_lshl_add_u64 v[210:211], s[18:19], 0, v[146:147]
	v_lshl_add_u64 v[164:165], s[76:77], 0, v[146:147]
	v_lshlrev_b64 v[146:147], 13, v[166:167]
	v_lshl_add_u64 v[146:147], v[164:165], 0, v[146:147]
	global_load_dwordx4 v[148:151], v[210:211], off offset:16 nt
	global_load_dwordx4 v[152:155], v[146:147], off offset:16 nt
	global_load_dwordx4 v[156:159], v[146:147], off nt
	global_load_dwordx4 v[174:177], v[146:147], off offset:528 nt
	global_load_dwordx4 v[178:181], v[146:147], off offset:512 nt
	v_or_b32_e32 v146, 16, v166
	v_ashrrev_i32_e32 v147, 31, v146
	v_lshlrev_b64 v[182:183], 13, v[146:147]
	v_lshl_add_u64 v[222:223], v[164:165], 0, v[182:183]
	v_lshl_add_u64 v[206:207], v[162:163], 0, s[16:17]
	global_load_dwordx4 v[182:185], v[222:223], off offset:16 nt
	global_load_dwordx4 v[186:189], v[222:223], off nt
	global_load_dwordx4 v[190:193], v[206:207], off offset:16 nt
	global_load_dwordx4 v[194:197], v[206:207], off offset:512 nt
	global_load_dwordx4 v[198:201], v[210:211], off offset:528 nt
	global_load_dwordx4 v[202:205], v[210:211], off offset:512 nt
	v_add_co_u32_e32 v162, vcc, s49, v162
	v_lshlrev_b64 v[144:145], 1, v[144:145]
	s_nop 0
	v_addc_co_u32_e32 v163, vcc, 0, v163, vcc
	global_load_dwordx4 v[206:209], v[206:207], off offset:528 nt
	s_nop 0
	global_load_dwordx4 v[210:213], v[210:211], off nt
	s_nop 0
	global_load_dwordx4 v[214:217], v[162:163], off nt
	global_load_dwordx4 v[218:221], v[222:223], off offset:512 nt
	s_nop 0
	global_load_dwordx4 v[222:225], v[222:223], off offset:528 nt
	v_lshlrev_b64 v[162:163], 12, v[166:167]
	v_lshl_add_u64 v[162:163], s[10:11], 0, v[162:163]
	v_lshlrev_b64 v[226:227], 12, v[146:147]
	v_lshl_add_u64 v[228:229], v[162:163], 0, v[144:145]
	s_andn2_b64 vcc, exec, s[4:5]
	s_mov_b64 s[4:5], -1
	s_waitcnt vmcnt(0)
	v_pk_mul_f32 v[234:235], v[154:155], s[20:21] op_sel_hi:[1,0]
	v_pk_mul_f32 v[230:231], v[158:159], s[20:21] op_sel_hi:[1,0]
	v_pk_mul_f32 v[232:233], v[156:157], s[20:21] op_sel_hi:[1,0]
	v_pk_mul_f32 v[236:237], v[152:153], s[20:21] op_sel_hi:[1,0]
	v_pk_mul_f32 v[180:181], v[180:181], s[20:21] op_sel_hi:[1,0]
	v_pk_mul_f32 v[178:179], v[178:179], s[20:21] op_sel_hi:[1,0]
	v_pk_mul_f32 v[176:177], v[176:177], s[20:21] op_sel_hi:[1,0]
	v_pk_mul_f32 v[174:175], v[174:175], s[20:21] op_sel_hi:[1,0]
	v_pk_add_f32 v[146:147], v[192:193], v[150:151]
	v_pk_add_f32 v[148:149], v[190:191], v[148:149]
	v_pk_add_f32 v[150:151], v[196:197], v[204:205]
	v_pk_add_f32 v[152:153], v[194:195], v[202:203]
	v_pk_add_f32 v[154:155], v[208:209], v[200:201]
	v_pk_add_f32 v[156:157], v[206:207], v[198:199]
	v_pk_add_f32 v[158:159], v[216:217], v[212:213]
	v_pk_add_f32 v[162:163], v[214:215], v[210:211]
	v_pk_fma_f32 v[126:127], v[126:127], v[146:147], v[234:235]
	v_pk_fma_f32 v[124:125], v[124:125], v[148:149], v[236:237]
	v_pk_fma_f32 v[110:111], v[110:111], v[150:151], v[180:181]
	v_pk_fma_f32 v[108:109], v[108:109], v[152:153], v[178:179]
	v_pk_fma_f32 v[176:177], v[106:107], v[154:155], v[176:177]
	v_pk_fma_f32 v[104:105], v[104:105], v[156:157], v[174:175]
	v_pk_fma_f32 v[122:123], v[122:123], v[158:159], v[230:231]
	v_pk_fma_f32 v[120:121], v[120:121], v[162:163], v[232:233]
	v_cvt_pk_f16_f32 v106, v124, v125
	v_cvt_pk_f16_f32 v107, v126, v127
	v_cvt_pk_f16_f32 v108, v108, v109
	v_cvt_pk_f16_f32 v109, v110, v111
	v_cvt_pk_f16_f32 v110, v104, v105
	v_cvt_pk_f16_f32 v111, v176, v177
	v_cvt_pk_f16_f32 v104, v120, v121
	v_cvt_pk_f16_f32 v105, v122, v123
	global_store_dwordx4 v[228:229], v[108:111], off offset:256
	global_store_dwordx4 v[228:229], v[104:107], off
	v_pk_mul_f32 v[188:189], v[188:189], s[20:21] op_sel_hi:[1,0]
	v_pk_mul_f32 v[108:109], v[218:219], s[20:21] op_sel_hi:[1,0]
	v_pk_mul_f32 v[106:107], v[220:221], s[20:21] op_sel_hi:[1,0]
	v_pk_fma_f32 v[100:101], v[100:101], v[152:153], v[108:109]
	v_pk_fma_f32 v[102:103], v[102:103], v[150:151], v[106:107]
	v_pk_mul_f32 v[106:107], v[224:225], s[20:21] op_sel_hi:[1,0]
	v_pk_mul_f32 v[108:109], v[222:223], s[20:21] op_sel_hi:[1,0]
	v_pk_mul_f32 v[186:187], v[186:187], s[20:21] op_sel_hi:[1,0]
	v_pk_mul_f32 v[184:185], v[184:185], s[20:21] op_sel_hi:[1,0]
	v_pk_mul_f32 v[182:183], v[182:183], s[20:21] op_sel_hi:[1,0]
	v_lshl_add_u64 v[104:105], s[10:11], 0, v[226:227]
	v_pk_fma_f32 v[106:107], v[98:99], v[154:155], v[106:107]
	v_pk_fma_f32 v[98:99], v[96:97], v[156:157], v[108:109]
	v_or_b32_e32 v174, 32, v166
	v_pk_fma_f32 v[118:119], v[118:119], v[146:147], v[184:185]
	v_pk_fma_f32 v[116:117], v[116:117], v[148:149], v[182:183]
	v_pk_fma_f32 v[114:115], v[114:115], v[158:159], v[188:189]
	v_pk_fma_f32 v[124:125], v[112:113], v[162:163], v[186:187]
	v_lshl_add_u64 v[104:105], v[104:105], 0, v[144:145]
	v_cvt_pk_f16_f32 v96, v100, v101
	v_cvt_pk_f16_f32 v97, v102, v103
	v_cvt_pk_f16_f32 v98, v98, v99
	v_cvt_pk_f16_f32 v99, v106, v107
	v_ashrrev_i32_e32 v175, 31, v174
	v_or_b32_e32 v176, 48, v166
	v_cvt_pk_f16_f32 v112, v116, v117
	v_cvt_pk_f16_f32 v110, v124, v125
	v_cvt_pk_f16_f32 v111, v114, v115
	v_cvt_pk_f16_f32 v113, v118, v119
	global_store_dwordx4 v[104:105], v[96:99], off offset:256
	v_ashrrev_i32_e32 v177, 31, v176
	global_store_dwordx4 v[104:105], v[110:113], off
	v_lshlrev_b64 v[96:97], 13, v[174:175]
	v_lshl_add_u64 v[108:109], v[164:165], 0, v[96:97]
	v_lshlrev_b64 v[112:113], 13, v[176:177]
	global_load_dwordx4 v[96:99], v[108:109], off nt
	global_load_dwordx4 v[100:103], v[108:109], off offset:16 nt
	global_load_dwordx4 v[104:107], v[108:109], off offset:528 nt
	s_nop 0
	global_load_dwordx4 v[108:111], v[108:109], off offset:512 nt
	v_lshl_add_u64 v[124:125], v[164:165], 0, v[112:113]
	global_load_dwordx4 v[112:115], v[124:125], off nt
	global_load_dwordx4 v[116:119], v[124:125], off offset:16 nt
	global_load_dwordx4 v[120:123], v[124:125], off offset:512 nt
	s_nop 0
	global_load_dwordx4 v[124:127], v[124:125], off offset:528 nt
	v_lshlrev_b64 v[174:175], 12, v[174:175]
	v_lshlrev_b64 v[176:177], 12, v[176:177]
	v_lshl_add_u64 v[174:175], s[10:11], 0, v[174:175]
	v_lshl_add_u64 v[176:177], s[10:11], 0, v[176:177]
	v_lshl_add_u64 v[174:175], v[174:175], 0, v[144:145]
	v_lshl_add_u64 v[176:177], v[176:177], 0, v[144:145]
	s_waitcnt vmcnt(7)
; __device__ __forceinline__ unsigned pkh2(float lo, float hi) { const f32x2 v = {lo, hi}; const f16x2_t h = __builtin_convertvector(v, f16x2_t); return __builtin_bit_cast(unsigned, h); }
;     __device__ __forceinline__ void operator()(const f32x4 (&acc)[2][2][4][2], const pg8::Unit& u, int wr, int wc, int fr, int fq) const {
;     ...
;                     for (int n = 0; n < 2; ++n) xb[mm][bj][n] = *(const f32x4*)(x + (size_t)(row0 + ai * 128 + (mp * 2 + mm) * 16) * 2048 + col0 + bj * 128 + 4 * n);
;             asm volatile("" ::: "memory");
; #pragma unroll
;             for (int mm = 0; mm < 2; ++mm) { const int m = mp * 2 + mm; const size_t ro = (size_t)(row0 + ai * 128 + m * 16) * 2048 + col0;
; #pragma unroll
;                 for (int bj = 0; bj < 2; ++bj) {
;                     const f32x4 v0 = xb[mm][bj][0] * 1.189207115002721f + gt[bj][0] * acc[ai][bj][m][0], v1 = xb[mm][bj][1] * 1.189207115002721f + gt[bj][1] * acc[ai][bj][m][1];
;                     u32x4 w; w.x = pkh2(v0[0], v0[1]); w.y = pkh2(v0[2], v0[3]); w.z = pkh2(v1[0], v1[1]); w.w = pkh2(v1[2], v1[3]);
;                     *(u32x4*)(out + ro + bj * 128) = w; } }
	v_pk_mul_f32 v[98:99], v[98:99], s[20:21] op_sel_hi:[1,0]
	v_pk_mul_f32 v[96:97], v[96:97], s[20:21] op_sel_hi:[1,0]
	s_waitcnt vmcnt(6)
	v_pk_mul_f32 v[102:103], v[102:103], s[20:21] op_sel_hi:[1,0]
	v_pk_mul_f32 v[100:101], v[100:101], s[20:21] op_sel_hi:[1,0]
	s_waitcnt vmcnt(4)
	v_pk_mul_f32 v[110:111], v[110:111], s[20:21] op_sel_hi:[1,0]
	v_pk_mul_f32 v[108:109], v[108:109], s[20:21] op_sel_hi:[1,0]
	v_pk_mul_f32 v[106:107], v[106:107], s[20:21] op_sel_hi:[1,0]
	v_pk_mul_f32 v[104:105], v[104:105], s[20:21] op_sel_hi:[1,0]
	s_waitcnt vmcnt(3)
	v_pk_mul_f32 v[114:115], v[114:115], s[20:21] op_sel_hi:[1,0]
	v_pk_mul_f32 v[112:113], v[112:113], s[20:21] op_sel_hi:[1,0]
	s_waitcnt vmcnt(2)
	v_pk_mul_f32 v[118:119], v[118:119], s[20:21] op_sel_hi:[1,0]
	v_pk_mul_f32 v[116:117], v[116:117], s[20:21] op_sel_hi:[1,0]
	s_waitcnt vmcnt(1)
	v_pk_mul_f32 v[122:123], v[122:123], s[20:21] op_sel_hi:[1,0]
	v_pk_mul_f32 v[120:121], v[120:121], s[20:21] op_sel_hi:[1,0]
	v_pk_fma_f32 v[94:95], v[94:95], v[158:159], v[98:99]
	v_pk_fma_f32 v[92:93], v[92:93], v[162:163], v[96:97]
	v_pk_fma_f32 v[90:91], v[90:91], v[146:147], v[102:103]
	v_pk_fma_f32 v[88:89], v[88:89], v[148:149], v[100:101]
	v_pk_fma_f32 v[78:79], v[78:79], v[150:151], v[110:111]
	v_pk_fma_f32 v[76:77], v[76:77], v[152:153], v[108:109]
	v_pk_fma_f32 v[96:97], v[74:75], v[154:155], v[106:107]
	v_pk_fma_f32 v[74:75], v[72:73], v[156:157], v[104:105]
	v_pk_fma_f32 v[86:87], v[86:87], v[158:159], v[114:115]
	v_pk_fma_f32 v[84:85], v[84:85], v[162:163], v[112:113]
	v_pk_fma_f32 v[82:83], v[82:83], v[146:147], v[118:119]
	v_pk_fma_f32 v[80:81], v[80:81], v[148:149], v[116:117]
	v_pk_fma_f32 v[98:99], v[70:71], v[150:151], v[122:123]
	v_pk_fma_f32 v[100:101], v[68:69], v[152:153], v[120:121]
	v_cvt_pk_f16_f32 v68, v92, v93
	v_cvt_pk_f16_f32 v69, v94, v95
	v_cvt_pk_f16_f32 v70, v88, v89
	v_cvt_pk_f16_f32 v71, v90, v91
	s_waitcnt vmcnt(0)
	v_pk_mul_f32 v[126:127], v[126:127], s[20:21] op_sel_hi:[1,0]
	v_cvt_pk_f16_f32 v72, v76, v77
	v_cvt_pk_f16_f32 v73, v78, v79
	v_cvt_pk_f16_f32 v74, v74, v75
	v_cvt_pk_f16_f32 v75, v96, v97
	v_cvt_pk_f16_f32 v76, v84, v85
	v_cvt_pk_f16_f32 v77, v86, v87
	v_cvt_pk_f16_f32 v78, v80, v81
	v_cvt_pk_f16_f32 v79, v82, v83
	global_store_dwordx4 v[174:175], v[68:71], off
	global_store_dwordx4 v[174:175], v[72:75], off offset:256
	global_store_dwordx4 v[176:177], v[76:79], off
	v_pk_mul_f32 v[68:69], v[124:125], s[20:21] op_sel_hi:[1,0]
	v_pk_fma_f32 v[70:71], v[66:67], v[154:155], v[126:127]
	v_pk_fma_f32 v[66:67], v[64:65], v[156:157], v[68:69]
	v_add_u32_e32 v96, 0x80, v166
	v_cvt_pk_f16_f32 v64, v100, v101
	v_cvt_pk_f16_f32 v65, v98, v99
	v_cvt_pk_f16_f32 v66, v66, v67
	v_cvt_pk_f16_f32 v67, v70, v71
	v_ashrrev_i32_e32 v97, 31, v96
	v_add_u32_e32 v98, 0x90, v166
	global_store_dwordx4 v[176:177], v[64:67], off offset:256
	v_ashrrev_i32_e32 v99, 31, v98
	v_lshlrev_b64 v[80:81], 13, v[98:99]
	v_lshlrev_b64 v[64:65], 13, v[96:97]
	v_lshl_add_u64 v[76:77], v[164:165], 0, v[64:65]
	global_load_dwordx4 v[64:67], v[76:77], off nt
	global_load_dwordx4 v[68:71], v[76:77], off offset:16 nt
	global_load_dwordx4 v[72:75], v[76:77], off offset:528 nt
	s_nop 0
	global_load_dwordx4 v[76:79], v[76:77], off offset:512 nt
	v_lshl_add_u64 v[92:93], v[164:165], 0, v[80:81]
	global_load_dwordx4 v[80:83], v[92:93], off nt
	global_load_dwordx4 v[84:87], v[92:93], off offset:16 nt
	global_load_dwordx4 v[88:91], v[92:93], off offset:512 nt
	s_nop 0
	global_load_dwordx4 v[92:95], v[92:93], off offset:528 nt
	v_lshlrev_b64 v[96:97], 12, v[96:97]
	v_add_u32_e32 v100, 0xa0, v166
	v_lshlrev_b64 v[98:99], 12, v[98:99]
	v_lshl_add_u64 v[96:97], s[10:11], 0, v[96:97]
	v_lshl_add_u64 v[98:99], s[10:11], 0, v[98:99]
	v_lshl_add_u64 v[96:97], v[96:97], 0, v[144:145]
	v_ashrrev_i32_e32 v101, 31, v100
	v_lshl_add_u64 v[98:99], v[98:99], 0, v[144:145]
	s_waitcnt vmcnt(7)
	v_pk_mul_f32 v[64:65], v[64:65], s[20:21] op_sel_hi:[1,0]
	v_pk_mul_f32 v[66:67], v[66:67], s[20:21] op_sel_hi:[1,0]
	s_waitcnt vmcnt(6)
	v_pk_mul_f32 v[70:71], v[70:71], s[20:21] op_sel_hi:[1,0]
	s_waitcnt vmcnt(4)
	v_pk_mul_f32 v[76:77], v[76:77], s[20:21] op_sel_hi:[1,0]
	s_waitcnt vmcnt(1)
	v_pk_mul_f32 v[90:91], v[90:91], s[20:21] op_sel_hi:[1,0]
	v_pk_mul_f32 v[68:69], v[68:69], s[20:21] op_sel_hi:[1,0]
	v_pk_mul_f32 v[88:89], v[88:89], s[20:21] op_sel_hi:[1,0]
	v_pk_fma_f32 v[60:61], v[60:61], v[162:163], v[64:65]
	v_pk_fma_f32 v[44:45], v[44:45], v[152:153], v[76:77]
	v_pk_fma_f32 v[64:65], v[38:39], v[150:151], v[90:91]
	v_pk_mul_f32 v[78:79], v[78:79], s[20:21] op_sel_hi:[1,0]
	v_pk_mul_f32 v[74:75], v[74:75], s[20:21] op_sel_hi:[1,0]
	v_pk_mul_f32 v[72:73], v[72:73], s[20:21] op_sel_hi:[1,0]
	v_pk_mul_f32 v[82:83], v[82:83], s[20:21] op_sel_hi:[1,0]
	v_pk_mul_f32 v[80:81], v[80:81], s[20:21] op_sel_hi:[1,0]
	v_pk_mul_f32 v[86:87], v[86:87], s[20:21] op_sel_hi:[1,0]
	v_pk_mul_f32 v[84:85], v[84:85], s[20:21] op_sel_hi:[1,0]
	s_waitcnt vmcnt(0)
; #define PG8_BAR __builtin_amdgcn_s_barrier()
; __device__ __forceinline__ unsigned pkh2(float lo, float hi) { const f32x2 v = {lo, hi}; const f16x2_t h = __builtin_convertvector(v, f16x2_t); return __builtin_bit_cast(unsigned, h); }
; template <class Epi, class Sched, bool ALIGN_EPI = false, bool SP2 = false>
; __device__ __forceinline__ void gemm_phase(PG8_LAS unsigned char* lds, const Gemm g, const Sched& S, const Epi& E) {
;     ...
;         cur = nxt; cA = nA; cB = nB; ++ui;
;         if constexpr (ALIGN_EPI) { if (wr == 1) PG8_BAR; }
;     __device__ __forceinline__ void operator()(const f32x4 (&acc)[2][2][4][2], const pg8::Unit& u, int wr, int wc, int fr, int fq) const {
;     ...
;                     for (int n = 0; n < 2; ++n) xb[mm][bj][n] = *(const f32x4*)(x + (size_t)(row0 + ai * 128 + (mp * 2 + mm) * 16) * 2048 + col0 + bj * 128 + 4 * n);
;             asm volatile("" ::: "memory");
; #pragma unroll
;             for (int mm = 0; mm < 2; ++mm) { const int m = mp * 2 + mm; const size_t ro = (size_t)(row0 + ai * 128 + m * 16) * 2048 + col0;
; #pragma unroll
;                 for (int bj = 0; bj < 2; ++bj) {
;                     const f32x4 v0 = xb[mm][bj][0] * 1.189207115002721f + gt[bj][0] * acc[ai][bj][m][0], v1 = xb[mm][bj][1] * 1.189207115002721f + gt[bj][1] * acc[ai][bj][m][1];
;                     u32x4 w; w.x = pkh2(v0[0], v0[1]); w.y = pkh2(v0[2], v0[3]); w.z = pkh2(v1[0], v1[1]); w.w = pkh2(v1[2], v1[3]);
;                     *(u32x4*)(out + ro + bj * 128) = w; } }
;           }
;     }
	v_pk_mul_f32 v[94:95], v[94:95], s[20:21] op_sel_hi:[1,0]
	v_pk_mul_f32 v[92:93], v[92:93], s[20:21] op_sel_hi:[1,0]
	v_pk_fma_f32 v[62:63], v[62:63], v[158:159], v[66:67]
	v_pk_fma_f32 v[58:59], v[58:59], v[146:147], v[70:71]
	v_pk_fma_f32 v[56:57], v[56:57], v[148:149], v[68:69]
	v_pk_fma_f32 v[66:67], v[36:37], v[152:153], v[88:89]
	v_cvt_pk_f16_f32 v36, v44, v45
	v_cvt_pk_f16_f32 v45, v64, v65
	v_add_u32_e32 v64, 0xb0, v166
	v_pk_fma_f32 v[46:47], v[46:47], v[150:151], v[78:79]
	v_pk_fma_f32 v[42:43], v[42:43], v[154:155], v[74:75]
	v_pk_fma_f32 v[40:41], v[40:41], v[156:157], v[72:73]
	v_pk_fma_f32 v[54:55], v[54:55], v[158:159], v[82:83]
	v_pk_fma_f32 v[52:53], v[52:53], v[162:163], v[80:81]
	v_pk_fma_f32 v[50:51], v[50:51], v[146:147], v[86:87]
	v_pk_fma_f32 v[48:49], v[48:49], v[148:149], v[84:85]
	v_pk_fma_f32 v[68:69], v[34:35], v[154:155], v[94:95]
	v_pk_fma_f32 v[70:71], v[32:33], v[156:157], v[92:93]
	v_cvt_pk_f16_f32 v32, v60, v61
	v_cvt_pk_f16_f32 v33, v62, v63
	v_cvt_pk_f16_f32 v34, v56, v57
	v_cvt_pk_f16_f32 v35, v58, v59
	v_ashrrev_i32_e32 v65, 31, v64
	v_cvt_pk_f16_f32 v37, v46, v47
	v_cvt_pk_f16_f32 v38, v40, v41
	v_cvt_pk_f16_f32 v39, v42, v43
	v_cvt_pk_f16_f32 v40, v52, v53
	v_cvt_pk_f16_f32 v41, v54, v55
	v_cvt_pk_f16_f32 v42, v48, v49
	v_cvt_pk_f16_f32 v43, v50, v51
	v_cvt_pk_f16_f32 v44, v66, v67
	v_cvt_pk_f16_f32 v46, v70, v71
	v_cvt_pk_f16_f32 v47, v68, v69
	global_store_dwordx4 v[96:97], v[32:35], off
	global_store_dwordx4 v[96:97], v[36:39], off offset:256
	global_store_dwordx4 v[98:99], v[40:43], off
	global_store_dwordx4 v[98:99], v[44:47], off offset:256
	v_lshlrev_b64 v[32:33], 13, v[100:101]
	v_lshlrev_b64 v[48:49], 13, v[64:65]
	v_lshl_add_u64 v[44:45], v[164:165], 0, v[32:33]
	v_lshl_add_u64 v[60:61], v[164:165], 0, v[48:49]
	global_load_dwordx4 v[32:35], v[44:45], off nt
	global_load_dwordx4 v[36:39], v[44:45], off offset:16 nt
	global_load_dwordx4 v[40:43], v[44:45], off offset:528 nt
	s_nop 0
	global_load_dwordx4 v[44:47], v[44:45], off offset:512 nt
	s_nop 0
	global_load_dwordx4 v[48:51], v[60:61], off nt
	global_load_dwordx4 v[52:55], v[60:61], off offset:16 nt
	global_load_dwordx4 v[56:59], v[60:61], off offset:512 nt
	s_nop 0
	global_load_dwordx4 v[60:63], v[60:61], off offset:528 nt
	v_lshlrev_b64 v[66:67], 12, v[100:101]
	v_lshlrev_b64 v[64:65], 12, v[64:65]
	v_lshl_add_u64 v[66:67], s[10:11], 0, v[66:67]
	v_lshl_add_u64 v[64:65], s[10:11], 0, v[64:65]
	v_lshl_add_u64 v[66:67], v[66:67], 0, v[144:145]
	v_lshl_add_u64 v[64:65], v[64:65], 0, v[144:145]
	s_waitcnt vmcnt(7)
	v_pk_mul_f32 v[34:35], v[34:35], s[20:21] op_sel_hi:[1,0]
	v_pk_mul_f32 v[32:33], v[32:33], s[20:21] op_sel_hi:[1,0]
	s_waitcnt vmcnt(6)
	v_pk_mul_f32 v[38:39], v[38:39], s[20:21] op_sel_hi:[1,0]
	v_pk_mul_f32 v[36:37], v[36:37], s[20:21] op_sel_hi:[1,0]
	s_waitcnt vmcnt(4)
	v_pk_mul_f32 v[46:47], v[46:47], s[20:21] op_sel_hi:[1,0]
	v_pk_mul_f32 v[44:45], v[44:45], s[20:21] op_sel_hi:[1,0]
	v_pk_mul_f32 v[42:43], v[42:43], s[20:21] op_sel_hi:[1,0]
	v_pk_mul_f32 v[40:41], v[40:41], s[20:21] op_sel_hi:[1,0]
	s_waitcnt vmcnt(3)
	v_pk_mul_f32 v[50:51], v[50:51], s[20:21] op_sel_hi:[1,0]
	v_pk_mul_f32 v[48:49], v[48:49], s[20:21] op_sel_hi:[1,0]
	s_waitcnt vmcnt(2)
	v_pk_mul_f32 v[54:55], v[54:55], s[20:21] op_sel_hi:[1,0]
	v_pk_mul_f32 v[52:53], v[52:53], s[20:21] op_sel_hi:[1,0]
	s_waitcnt vmcnt(1)
	v_pk_mul_f32 v[58:59], v[58:59], s[20:21] op_sel_hi:[1,0]
	v_pk_mul_f32 v[56:57], v[56:57], s[20:21] op_sel_hi:[1,0]
	s_waitcnt vmcnt(0)
	v_pk_mul_f32 v[62:63], v[62:63], s[20:21] op_sel_hi:[1,0]
	v_pk_mul_f32 v[60:61], v[60:61], s[20:21] op_sel_hi:[1,0]
	v_pk_fma_f32 v[30:31], v[30:31], v[158:159], v[34:35]
	v_pk_fma_f32 v[28:29], v[28:29], v[162:163], v[32:33]
	v_pk_fma_f32 v[26:27], v[26:27], v[146:147], v[38:39]
	v_pk_fma_f32 v[24:25], v[24:25], v[148:149], v[36:37]
	v_pk_fma_f32 v[14:15], v[14:15], v[150:151], v[46:47]
	v_pk_fma_f32 v[12:13], v[12:13], v[152:153], v[44:45]
	v_pk_fma_f32 v[10:11], v[10:11], v[154:155], v[42:43]
	v_pk_fma_f32 v[8:9], v[8:9], v[156:157], v[40:41]
	v_pk_fma_f32 v[22:23], v[22:23], v[158:159], v[50:51]
	v_pk_fma_f32 v[20:21], v[20:21], v[162:163], v[48:49]
	v_pk_fma_f32 v[18:19], v[18:19], v[146:147], v[54:55]
	v_pk_fma_f32 v[16:17], v[16:17], v[148:149], v[52:53]
	v_pk_fma_f32 v[32:33], v[6:7], v[150:151], v[58:59]
	v_pk_fma_f32 v[34:35], v[4:5], v[152:153], v[56:57]
	v_pk_fma_f32 v[36:37], v[2:3], v[154:155], v[62:63]
	v_pk_fma_f32 v[38:39], v[0:1], v[156:157], v[60:61]
	v_cvt_pk_f16_f32 v0, v28, v29
	v_cvt_pk_f16_f32 v1, v30, v31
	v_cvt_pk_f16_f32 v2, v24, v25
	v_cvt_pk_f16_f32 v3, v26, v27
	v_cvt_pk_f16_f32 v4, v12, v13
	v_cvt_pk_f16_f32 v5, v14, v15
	v_cvt_pk_f16_f32 v6, v8, v9
	v_cvt_pk_f16_f32 v7, v10, v11
	v_cvt_pk_f16_f32 v8, v20, v21
	v_cvt_pk_f16_f32 v9, v22, v23
	v_cvt_pk_f16_f32 v10, v16, v17
	v_cvt_pk_f16_f32 v11, v18, v19
	v_cvt_pk_f16_f32 v12, v34, v35
	v_cvt_pk_f16_f32 v13, v32, v33
	v_cvt_pk_f16_f32 v14, v38, v39
	v_cvt_pk_f16_f32 v15, v36, v37
	global_store_dwordx4 v[66:67], v[0:3], off
	global_store_dwordx4 v[66:67], v[4:7], off offset:256
	global_store_dwordx4 v[64:65], v[8:11], off
	global_store_dwordx4 v[64:65], v[12:15], off offset:256
	s_cbranch_vccnz .LBB0_935
	s_andn2_b64 vcc, exec, s[8:9]
	s_cbranch_vccnz .LBB0_934
	s_barrier
	s_branch .LBB0_934

; __device__ __forceinline__ f32x2 unpkh2(unsigned u) { return __builtin_convertvector(__builtin_bit_cast(f16x2_t, u), f32x2); }
; __device__ __forceinline__ void phase_ln(const Args& a, int lane, int wave) {
;     const bf16_t* R = (const bf16_t*)(a.ws + WS_BQ);
;     for (int r = blockIdx.x * 8 + wave; r < MLAT; r += gridDim.x * 8) {
;         const u32x2* rr = (const u32x2*)(R + (size_t)r * 2048) + lane;
;         f32x4* xr = (f32x4*)(a.out + (size_t)r * 2048) + lane;
;         u32x2 w[8]; f32x4 v[8]; float s = 0.f;
; #pragma unroll
;         for (int q = 0; q < 8; ++q) w[q] = __builtin_nontemporal_load(rr + 64 * q);
; #pragma unroll
;         for (int q = 0; q < 8; ++q) { { const f32x2 p0 = unpkh2(w[q].x), p1 = unpkh2(w[q].y); v[q] = (f32x4){p0.x, p0.y, p1.x, p1.y}; } s += (v[q].x + v[q].y) + (v[q].z + v[q].w); }
;         const float mean = wave_sum(s) * (1.f / 2048.f); float s2 = 0.f;
; #pragma unroll
;         for (int q = 0; q < 8; ++q) { v[q] = v[q] - mean; s2 += (v[q].x * v[q].x + v[q].y * v[q].y) + (v[q].z * v[q].z + v[q].w * v[q].w); }
;         const float rstd = rsqrtf(wave_sum(s2) * (1.f / 2048.f) + 1e-6f);
;         const f32x4* gg = (const f32x4*)a.ln_g + lane; const f32x4* bb = (const f32x4*)a.ln_b + lane;
; #pragma unroll
;         for (int q = 0; q < 8; ++q) __builtin_nontemporal_store(v[q] * rstd * gg[64 * q] + bb[64 * q], xr + 64 * q);
.LBB0_1004:
	s_cmp_lt_i32 s96, 10
	s_cselect_b64 s[6:7], -1, 0
	s_and_b64 s[4:5], s[6:7], s[4:5]
	s_andn2_b64 vcc, exec, s[4:5]
	s_cbranch_vccnz .LBB0_1008
	s_lshl_b32 s1, s2, 3
	s_add_i32 s2, s0, s1
	s_cmpk_gt_i32 s2, 0x7fff
	s_cbranch_scc1 .LBB0_1008
	v_lshlrev_b32_e32 v1, 3, v160
	v_lshlrev_b32_e32 v2, 4, v160
	s_add_u32 s8, s72, 0x1000
	s_addc_u32 s9, s73, 0
	s_add_u32 s10, s74, 0x1000
	s_addc_u32 s11, s75, 0
	global_load_dwordx4 v[64:67], v2, s[72:73]
	global_load_dwordx4 v[68:71], v2, s[72:73] offset:1024
	global_load_dwordx4 v[72:75], v2, s[72:73] offset:2048
	global_load_dwordx4 v[76:79], v2, s[72:73] offset:3072
	global_load_dwordx4 v[80:83], v2, s[8:9]
	global_load_dwordx4 v[84:87], v2, s[8:9] offset:1024
	global_load_dwordx4 v[88:91], v2, s[8:9] offset:2048
	global_load_dwordx4 v[92:95], v2, s[8:9] offset:3072
	global_load_dwordx4 v[96:99], v2, s[74:75]
	global_load_dwordx4 v[100:103], v2, s[74:75] offset:1024
	global_load_dwordx4 v[104:107], v2, s[74:75] offset:2048
	global_load_dwordx4 v[108:111], v2, s[74:75] offset:3072
	global_load_dwordx4 v[112:115], v2, s[10:11]
	global_load_dwordx4 v[116:119], v2, s[10:11] offset:1024
	global_load_dwordx4 v[120:123], v2, s[10:11] offset:2048
	global_load_dwordx4 v[124:127], v2, s[10:11] offset:3072
	v_readlane_b32 s12, v252, 0
	v_readlane_b32 s13, v252, 1
	s_nop 3
	s_load_dword s14, s[12:13], 0x98
	s_add_u32 s4, s94, 0x10500000
	s_addc_u32 s5, s95, 0
	s_mov_b32 s22, 0xba000000
	s_mov_b32 s23, 0x800000
	v_mov_b32_e32 v10, 0x358637bd
	s_waitcnt lgkmcnt(0)
	s_lshl_b32 s14, s14, 3
	s_ashr_i32 s3, s2, 31
	s_lshl_b64 s[6:7], s[2:3], 12
	s_add_u32 s18, s4, s6
	s_addc_u32 s19, s5, s7
	global_load_dwordx2 v[24:25], v1, s[18:19]
	global_load_dwordx2 v[26:27], v1, s[18:19] offset:512
	global_load_dwordx2 v[28:29], v1, s[18:19] offset:1024
	global_load_dwordx2 v[30:31], v1, s[18:19] offset:1536
	global_load_dwordx2 v[32:33], v1, s[18:19] offset:2048
	global_load_dwordx2 v[34:35], v1, s[18:19] offset:2560
	global_load_dwordx2 v[36:37], v1, s[18:19] offset:3072
	global_load_dwordx2 v[38:39], v1, s[18:19] offset:3584
	s_waitcnt vmcnt(0)
	s_branch .Lln9_body
.Lln9_loop:
	s_waitcnt vmcnt(8)
.Lln9_body:
	v_cvt_f32_f16_e32 v128, v24
	v_cvt_f32_f16_sdwa v129, v24 dst_sel:DWORD dst_unused:UNUSED_PAD src0_sel:WORD_1
	v_cvt_f32_f16_e32 v130, v25
	v_cvt_f32_f16_sdwa v131, v25 dst_sel:DWORD dst_unused:UNUSED_PAD src0_sel:WORD_1
	v_cvt_f32_f16_e32 v132, v26
	v_cvt_f32_f16_sdwa v133, v26 dst_sel:DWORD dst_unused:UNUSED_PAD src0_sel:WORD_1
	v_cvt_f32_f16_e32 v134, v27
	v_cvt_f32_f16_sdwa v135, v27 dst_sel:DWORD dst_unused:UNUSED_PAD src0_sel:WORD_1
	v_cvt_f32_f16_e32 v136, v28
	v_cvt_f32_f16_sdwa v137, v28 dst_sel:DWORD dst_unused:UNUSED_PAD src0_sel:WORD_1
	v_cvt_f32_f16_e32 v138, v29
	v_cvt_f32_f16_sdwa v139, v29 dst_sel:DWORD dst_unused:UNUSED_PAD src0_sel:WORD_1
	v_cvt_f32_f16_e32 v140, v30
	v_cvt_f32_f16_sdwa v141, v30 dst_sel:DWORD dst_unused:UNUSED_PAD src0_sel:WORD_1
	v_cvt_f32_f16_e32 v142, v31
	v_cvt_f32_f16_sdwa v143, v31 dst_sel:DWORD dst_unused:UNUSED_PAD src0_sel:WORD_1
	v_cvt_f32_f16_e32 v144, v32
	v_cvt_f32_f16_sdwa v145, v32 dst_sel:DWORD dst_unused:UNUSED_PAD src0_sel:WORD_1
	v_cvt_f32_f16_e32 v146, v33
	v_cvt_f32_f16_sdwa v147, v33 dst_sel:DWORD dst_unused:UNUSED_PAD src0_sel:WORD_1
	v_cvt_f32_f16_e32 v148, v34
	v_cvt_f32_f16_sdwa v149, v34 dst_sel:DWORD dst_unused:UNUSED_PAD src0_sel:WORD_1
	v_cvt_f32_f16_e32 v150, v35
	v_cvt_f32_f16_sdwa v151, v35 dst_sel:DWORD dst_unused:UNUSED_PAD src0_sel:WORD_1
	v_cvt_f32_f16_e32 v152, v36
	v_cvt_f32_f16_sdwa v153, v36 dst_sel:DWORD dst_unused:UNUSED_PAD src0_sel:WORD_1
	v_cvt_f32_f16_e32 v154, v37
	v_cvt_f32_f16_sdwa v155, v37 dst_sel:DWORD dst_unused:UNUSED_PAD src0_sel:WORD_1
	v_cvt_f32_f16_e32 v156, v38
	v_cvt_f32_f16_sdwa v157, v38 dst_sel:DWORD dst_unused:UNUSED_PAD src0_sel:WORD_1
	v_cvt_f32_f16_e32 v158, v39
	v_cvt_f32_f16_sdwa v159, v39 dst_sel:DWORD dst_unused:UNUSED_PAD src0_sel:WORD_1
	s_add_i32 s15, s2, s14
	s_cmp_lt_i32 s15, 0x8000
	s_cbranch_scc0 .Lln9_nopf
	s_ashr_i32 s16, s15, 31
	s_mov_b32 s24, s15
	s_mov_b32 s25, s16
	s_lshl_b64 s[6:7], s[24:25], 12
	s_add_u32 s18, s4, s6
	s_addc_u32 s19, s5, s7
	global_load_dwordx2 v[24:25], v1, s[18:19]
	global_load_dwordx2 v[26:27], v1, s[18:19] offset:512
	global_load_dwordx2 v[28:29], v1, s[18:19] offset:1024
	global_load_dwordx2 v[30:31], v1, s[18:19] offset:1536
	global_load_dwordx2 v[32:33], v1, s[18:19] offset:2048
	global_load_dwordx2 v[34:35], v1, s[18:19] offset:2560
	global_load_dwordx2 v[36:37], v1, s[18:19] offset:3072
	global_load_dwordx2 v[38:39], v1, s[18:19] offset:3584
; __device__ __forceinline__ f32x2 unpkh2(unsigned u) { return __builtin_convertvector(__builtin_bit_cast(f16x2_t, u), f32x2); }
; __device__ __forceinline__ float wave_sum(float v) {
; #pragma unroll
;     for (int o = 1; o < 64; o <<= 1) v += __shfl_xor(v, o);
;     return v;
; }
; __device__ __forceinline__ void phase_ln(const Args& a, int lane, int wave) {
;     ...
;         for (int q = 0; q < 8; ++q) { { const f32x2 p0 = unpkh2(w[q].x), p1 = unpkh2(w[q].y); v[q] = (f32x4){p0.x, p0.y, p1.x, p1.y}; } s += (v[q].x + v[q].y) + (v[q].z + v[q].w); }
;         const float mean = wave_sum(s) * (1.f / 2048.f); float s2 = 0.f;
; #pragma unroll
;         for (int q = 0; q < 8; ++q) { v[q] = v[q] - mean; s2 += (v[q].x * v[q].x + v[q].y * v[q].y) + (v[q].z * v[q].z + v[q].w * v[q].w); }
;         const float rstd = rsqrtf(wave_sum(s2) * (1.f / 2048.f) + 1e-6f);
.Lln9_nopf:
	v_mov_b32_e32 v3, 0
	v_add_f32_e32 v4, v128, v129
	v_add_f32_e32 v5, v130, v131
	v_add_f32_e32 v4, v4, v5
	v_add_f32_e32 v3, v3, v4
	v_add_f32_e32 v4, v132, v133
	v_add_f32_e32 v5, v134, v135
	v_add_f32_e32 v4, v4, v5
	v_add_f32_e32 v3, v3, v4
	v_add_f32_e32 v4, v136, v137
	v_add_f32_e32 v5, v138, v139
	v_add_f32_e32 v4, v4, v5
	v_add_f32_e32 v3, v3, v4
	v_add_f32_e32 v4, v140, v141
	v_add_f32_e32 v5, v142, v143
	v_add_f32_e32 v4, v4, v5
	v_add_f32_e32 v3, v3, v4
	v_add_f32_e32 v4, v144, v145
	v_add_f32_e32 v5, v146, v147
	v_add_f32_e32 v4, v4, v5
	v_add_f32_e32 v3, v3, v4
	v_add_f32_e32 v4, v148, v149
	v_add_f32_e32 v5, v150, v151
	v_add_f32_e32 v4, v4, v5
	v_add_f32_e32 v3, v3, v4
	v_add_f32_e32 v4, v152, v153
	v_add_f32_e32 v5, v154, v155
	v_add_f32_e32 v4, v4, v5
	v_add_f32_e32 v3, v3, v4
	v_add_f32_e32 v4, v156, v157
	v_add_f32_e32 v5, v158, v159
	v_add_f32_e32 v4, v4, v5
	v_add_f32_e32 v3, v3, v4
	s_nop 1
	v_add_f32_dpp v6, v3, v3 quad_perm:[1,0,3,2] row_mask:0xf bank_mask:0xf
	s_nop 1
	v_add_f32_dpp v3, v6, v6 quad_perm:[2,3,0,1] row_mask:0xf bank_mask:0xf
	s_nop 1
	v_add_f32_dpp v6, v3, v3 row_half_mirror row_mask:0xf bank_mask:0xf
	s_nop 1
	v_add_f32_dpp v3, v6, v6 row_mirror row_mask:0xf bank_mask:0xf
	ds_swizzle_b32 v6, v3 offset:0x401f
	s_waitcnt lgkmcnt(0)
	v_add_f32_e32 v3, v3, v6
	s_nop 0
	v_readlane_b32 s20, v3, 0
	v_readlane_b32 s21, v3, 32
	s_nop 1
	v_mov_b32_e32 v6, s21
	v_add_f32_e32 v3, s20, v6
	v_fma_f32 v128, v3, s22, v128
	v_fma_f32 v129, v3, s22, v129
	v_fma_f32 v130, v3, s22, v130
	v_fma_f32 v131, v3, s22, v131
	v_fma_f32 v132, v3, s22, v132
	v_fma_f32 v133, v3, s22, v133
	v_fma_f32 v134, v3, s22, v134
	v_fma_f32 v135, v3, s22, v135
	v_fma_f32 v136, v3, s22, v136
	v_fma_f32 v137, v3, s22, v137
	v_fma_f32 v138, v3, s22, v138
	v_fma_f32 v139, v3, s22, v139
	v_fma_f32 v140, v3, s22, v140
	v_fma_f32 v141, v3, s22, v141
	v_fma_f32 v142, v3, s22, v142
	v_fma_f32 v143, v3, s22, v143
	v_fma_f32 v144, v3, s22, v144
	v_fma_f32 v145, v3, s22, v145
	v_fma_f32 v146, v3, s22, v146
	v_fma_f32 v147, v3, s22, v147
	v_fma_f32 v148, v3, s22, v148
	v_fma_f32 v149, v3, s22, v149
	v_fma_f32 v150, v3, s22, v150
	v_fma_f32 v151, v3, s22, v151
	v_fma_f32 v152, v3, s22, v152
	v_fma_f32 v153, v3, s22, v153
	v_fma_f32 v154, v3, s22, v154
	v_fma_f32 v155, v3, s22, v155
	v_fma_f32 v156, v3, s22, v156
	v_fma_f32 v157, v3, s22, v157
	v_fma_f32 v158, v3, s22, v158
	v_fma_f32 v159, v3, s22, v159
	v_mov_b32_e32 v3, 0
	v_mul_f32_e32 v4, v128, v128
	v_mul_f32_e32 v5, v130, v130
	v_fmac_f32_e32 v4, v129, v129
	v_fmac_f32_e32 v5, v131, v131
	v_add_f32_e32 v4, v4, v5
	v_add_f32_e32 v3, v3, v4
	v_mul_f32_e32 v4, v132, v132
	v_mul_f32_e32 v5, v134, v134
	v_fmac_f32_e32 v4, v133, v133
	v_fmac_f32_e32 v5, v135, v135
	v_add_f32_e32 v4, v4, v5
	v_add_f32_e32 v3, v3, v4
	v_mul_f32_e32 v4, v136, v136
	v_mul_f32_e32 v5, v138, v138
	v_fmac_f32_e32 v4, v137, v137
	v_fmac_f32_e32 v5, v139, v139
	v_add_f32_e32 v4, v4, v5
	v_add_f32_e32 v3, v3, v4
	v_mul_f32_e32 v4, v140, v140
	v_mul_f32_e32 v5, v142, v142
	v_fmac_f32_e32 v4, v141, v141
	v_fmac_f32_e32 v5, v143, v143
	v_add_f32_e32 v4, v4, v5
	v_add_f32_e32 v3, v3, v4
	v_mul_f32_e32 v4, v144, v144
	v_mul_f32_e32 v5, v146, v146
	v_fmac_f32_e32 v4, v145, v145
	v_fmac_f32_e32 v5, v147, v147
	v_add_f32_e32 v4, v4, v5
	v_add_f32_e32 v3, v3, v4
	v_mul_f32_e32 v4, v148, v148
	v_mul_f32_e32 v5, v150, v150
	v_fmac_f32_e32 v4, v149, v149
	v_fmac_f32_e32 v5, v151, v151
	v_add_f32_e32 v4, v4, v5
	v_add_f32_e32 v3, v3, v4
	v_mul_f32_e32 v4, v152, v152
	v_mul_f32_e32 v5, v154, v154
	v_fmac_f32_e32 v4, v153, v153
	v_fmac_f32_e32 v5, v155, v155
	v_add_f32_e32 v4, v4, v5
	v_add_f32_e32 v3, v3, v4
	v_mul_f32_e32 v4, v156, v156
	v_mul_f32_e32 v5, v158, v158
	v_fmac_f32_e32 v4, v157, v157
	v_fmac_f32_e32 v5, v159, v159
	v_add_f32_e32 v4, v4, v5
	v_add_f32_e32 v3, v3, v4
	s_nop 1
	v_add_f32_dpp v6, v3, v3 quad_perm:[1,0,3,2] row_mask:0xf bank_mask:0xf
	s_nop 1
	v_add_f32_dpp v3, v6, v6 quad_perm:[2,3,0,1] row_mask:0xf bank_mask:0xf
	s_nop 1
	v_add_f32_dpp v6, v3, v3 row_half_mirror row_mask:0xf bank_mask:0xf
	s_nop 1
	v_add_f32_dpp v3, v6, v6 row_mirror row_mask:0xf bank_mask:0xf
	ds_swizzle_b32 v6, v3 offset:0x401f
	s_waitcnt lgkmcnt(0)
; __device__ __forceinline__ void phase_ln(const Args& a, int lane, int wave) {
;     ...
;         const float rstd = rsqrtf(wave_sum(s2) * (1.f / 2048.f) + 1e-6f);
;         const f32x4* gg = (const f32x4*)a.ln_g + lane; const f32x4* bb = (const f32x4*)a.ln_b + lane;
; #pragma unroll
;         for (int q = 0; q < 8; ++q) __builtin_nontemporal_store(v[q] * rstd * gg[64 * q] + bb[64 * q], xr + 64 * q);
	v_add_f32_e32 v3, v3, v6
	s_nop 0
	v_readlane_b32 s20, v3, 0
	v_readlane_b32 s21, v3, 32
	s_nop 1
	v_mov_b32_e32 v6, s21
	v_add_f32_e32 v3, s20, v6
	v_fmamk_f32 v3, v3, 0x3a000000, v10
	v_mul_f32_e32 v4, 0x4b800000, v3
	v_cmp_gt_f32_e32 vcc, s23, v3
	s_nop 1
	v_cndmask_b32_e32 v3, v3, v4, vcc
	v_rsq_f32_e32 v3, v3
	s_nop 0
	v_mul_f32_e32 v4, 0x45800000, v3
	v_cndmask_b32_e32 v8, v3, v4, vcc
	s_ashr_i32 s3, s2, 31
	s_lshl_b64 s[6:7], s[2:3], 13
	s_add_u32 s16, s92, s6
	s_addc_u32 s17, s93, s7
	s_add_u32 s26, s16, 0x1000
	s_addc_u32 s27, s17, 0
	v_pk_mul_f32 v[40:41], v[128:129], v[8:9] op_sel_hi:[1,0]
	v_pk_mul_f32 v[42:43], v[130:131], v[8:9] op_sel_hi:[1,0]
	v_pk_fma_f32 v[40:41], v[64:65], v[40:41], v[96:97]
	v_pk_fma_f32 v[42:43], v[66:67], v[42:43], v[98:99]
	global_store_dwordx4 v2, v[40:43], s[16:17] nt
	v_pk_mul_f32 v[44:45], v[132:133], v[8:9] op_sel_hi:[1,0]
	v_pk_mul_f32 v[46:47], v[134:135], v[8:9] op_sel_hi:[1,0]
	v_pk_fma_f32 v[44:45], v[68:69], v[44:45], v[100:101]
	v_pk_fma_f32 v[46:47], v[70:71], v[46:47], v[102:103]
	global_store_dwordx4 v2, v[44:47], s[16:17] offset:1024 nt
	v_pk_mul_f32 v[48:49], v[136:137], v[8:9] op_sel_hi:[1,0]
	v_pk_mul_f32 v[50:51], v[138:139], v[8:9] op_sel_hi:[1,0]
	v_pk_fma_f32 v[48:49], v[72:73], v[48:49], v[104:105]
	v_pk_fma_f32 v[50:51], v[74:75], v[50:51], v[106:107]
	global_store_dwordx4 v2, v[48:51], s[16:17] offset:2048 nt
	v_pk_mul_f32 v[52:53], v[140:141], v[8:9] op_sel_hi:[1,0]
	v_pk_mul_f32 v[54:55], v[142:143], v[8:9] op_sel_hi:[1,0]
	v_pk_fma_f32 v[52:53], v[76:77], v[52:53], v[108:109]
	v_pk_fma_f32 v[54:55], v[78:79], v[54:55], v[110:111]
	global_store_dwordx4 v2, v[52:55], s[16:17] offset:3072 nt
	v_pk_mul_f32 v[40:41], v[144:145], v[8:9] op_sel_hi:[1,0]
	v_pk_mul_f32 v[42:43], v[146:147], v[8:9] op_sel_hi:[1,0]
	v_pk_fma_f32 v[40:41], v[80:81], v[40:41], v[112:113]
	v_pk_fma_f32 v[42:43], v[82:83], v[42:43], v[114:115]
	global_store_dwordx4 v2, v[40:43], s[26:27] nt
	v_pk_mul_f32 v[44:45], v[148:149], v[8:9] op_sel_hi:[1,0]
	v_pk_mul_f32 v[46:47], v[150:151], v[8:9] op_sel_hi:[1,0]
	v_pk_fma_f32 v[44:45], v[84:85], v[44:45], v[116:117]
	v_pk_fma_f32 v[46:47], v[86:87], v[46:47], v[118:119]
	global_store_dwordx4 v2, v[44:47], s[26:27] offset:1024 nt
	v_pk_mul_f32 v[48:49], v[152:153], v[8:9] op_sel_hi:[1,0]
	v_pk_mul_f32 v[50:51], v[154:155], v[8:9] op_sel_hi:[1,0]
	v_pk_fma_f32 v[48:49], v[88:89], v[48:49], v[120:121]
	v_pk_fma_f32 v[50:51], v[90:91], v[50:51], v[122:123]
	global_store_dwordx4 v2, v[48:51], s[26:27] offset:2048 nt
	v_pk_mul_f32 v[52:53], v[156:157], v[8:9] op_sel_hi:[1,0]
	v_pk_mul_f32 v[54:55], v[158:159], v[8:9] op_sel_hi:[1,0]
	v_pk_fma_f32 v[52:53], v[92:93], v[52:53], v[124:125]
	v_pk_fma_f32 v[54:55], v[94:95], v[54:55], v[126:127]
	global_store_dwordx4 v2, v[52:55], s[26:27] offset:3072 nt
	s_mov_b32 s2, s15
	s_cmp_lt_i32 s2, 0x8000
	s_cbranch_scc1 .Lln9_loop
